# grid barrier: all waiters poll the monotonic cross-XCD arrival counter (>= (gen+1)*nx) instead of a generation word bumped after the last leader's atomic returns
# speedup vs baseline: 1.0415x; 1.0028x over previous
.LBB0_55:
	s_or_b64 exec, exec, s[8:9]
	v_cvt_f32_u32_e32 v4, v2
	s_waitcnt vmcnt(0)
	v_readfirstlane_b32 s0, v3
	v_sub_u32_e32 v3, 0, v2
	v_rcp_iflag_f32_e32 v4, v4
	v_add_u32_e32 v5, s0, v1
	v_mul_f32_e32 v4, 0x4f7ffffe, v4
	v_cvt_u32_f32_e32 v4, v4
	v_mul_lo_u32 v1, v3, v4
	v_mul_hi_u32 v1, v4, v1
	v_add_u32_e32 v1, v4, v1
	v_mul_hi_u32 v1, v5, v1
	v_mul_lo_u32 v3, v1, v2
	v_sub_u32_e32 v3, v5, v3
	v_add_u32_e32 v4, 1, v1
	v_cmp_ge_u32_e32 vcc, v3, v2
	s_nop 1
	v_cndmask_b32_e32 v1, v1, v4, vcc
	v_sub_u32_e32 v4, v3, v2
	v_cndmask_b32_e32 v3, v3, v4, vcc
	v_add_u32_e32 v4, 1, v1
	v_cmp_ge_u32_e32 vcc, v3, v2
	v_add_u32_e32 v3, 1, v5
	s_nop 0
	v_cndmask_b32_e32 v1, v1, v4, vcc
	v_mul_lo_u32 v4, v2, v1
	v_add_u32_e32 v2, v4, v2
	v_cmp_ne_u32_e32 vcc, v3, v2
	s_and_saveexec_b64 s[0:1], vcc
	s_xor_b64 s[6:7], exec, s[0:1]
	s_cbranch_execz .LBB0_69
	s_waitcnt lgkmcnt(0)
	s_add_u32 s16, s92, 0x4400
	s_addc_u32 s17, s93, 0
	v_mad_u32_u24 v1, v1, v0, v0
	v_mov_b32_e32 v0, 0
	global_load_dword v0, v0, s[16:17] sc1
	s_waitcnt vmcnt(0)
	v_cmp_lt_u32_e32 vcc, v0, v1
	s_and_saveexec_b64 s[8:9], vcc
	s_cbranch_execz .LBB0_68
	s_add_u32 s14, s92, 0x1200
	s_addc_u32 s15, s93, 0
	s_mov_b32 s0, 1
	s_mov_b64 s[18:19], 0
	v_mov_b32_e32 v0, 0
	s_branch .LBB0_59

.LBB0_63:
	global_load_dword v2, v0, s[16:17] sc1
	s_add_i32 s0, s0, 1
	s_mov_b64 s[30:31], -1
	s_waitcnt vmcnt(0)
	v_cmp_ge_u32_e32 vcc, v2, v1
	s_orn2_b64 s[22:23], vcc, exec
	s_branch .LBB0_58

.LBB0_72:
	s_or_b64 exec, exec, s[8:9]
	v_cvt_f32_u32_e32 v3, v0
	s_waitcnt vmcnt(0)
	v_readfirstlane_b32 s0, v2
	s_add_u32 s8, s92, 0x4500
	s_addc_u32 s9, s93, 0
	v_rcp_iflag_f32_e32 v3, v3
	v_add_u32_e32 v1, s0, v1
	v_add_u32_e32 v4, 1, v1
	s_mov_b64 s[14:15], -1
	v_mul_f32_e32 v2, 0x4f7ffffe, v3
	v_cvt_u32_f32_e32 v2, v2
	v_sub_u32_e32 v3, 0, v0
	v_mul_lo_u32 v3, v3, v2
	v_mul_hi_u32 v3, v2, v3
	v_add_u32_e32 v2, v2, v3
	v_mul_hi_u32 v2, v1, v2
	v_mul_lo_u32 v3, v2, v0
	v_sub_u32_e32 v1, v1, v3
	v_add_u32_e32 v5, 1, v2
	v_cmp_ge_u32_e32 vcc, v1, v0
	v_sub_u32_e32 v3, v1, v0
	s_nop 0
	v_cndmask_b32_e32 v2, v2, v5, vcc
	v_cndmask_b32_e32 v1, v1, v3, vcc
	v_add_u32_e32 v3, 1, v2
	v_cmp_ge_u32_e32 vcc, v1, v0
	s_nop 1
	v_cndmask_b32_e32 v2, v2, v3, vcc
	v_mul_lo_u32 v1, v0, v2
	v_add_u32_e32 v0, v1, v0
	v_cmp_ne_u32_e32 vcc, v4, v0
	v_mov_b32_e32 v2, v0
	v_mov_b64_e32 v[0:1], s[8:9]
	s_and_saveexec_b64 s[6:7], vcc
	s_cbranch_execz .LBB0_84
	v_mov_b32_e32 v0, 0
	global_load_dword v1, v0, s[8:9] offset:-256 sc1
	s_mov_b64 s[18:19], 0
	s_waitcnt vmcnt(0)
	v_cmp_lt_u32_e32 vcc, v1, v2
	s_and_saveexec_b64 s[16:17], vcc
	s_cbranch_execz .LBB0_83
	s_add_u32 s14, s92, 0x1200
	s_addc_u32 s15, s93, 0
	s_mov_b32 s0, 1
	s_branch .LBB0_76

.LBB0_80:
	global_load_dword v1, v0, s[8:9] offset:-256 sc1
	s_add_i32 s0, s0, 1
	s_mov_b64 s[22:23], -1
	s_waitcnt vmcnt(0)
	v_cmp_ge_u32_e32 vcc, v1, v2
	s_orn2_b64 s[34:35], vcc, exec
	s_branch .LBB0_75

.LBB0_311:
	s_or_b64 exec, exec, s[8:9]
	v_cvt_f32_u32_e32 v4, v2
	s_waitcnt vmcnt(0)
	v_readfirstlane_b32 s0, v3
	v_sub_u32_e32 v3, 0, v2
	v_rcp_iflag_f32_e32 v4, v4
	v_add_u32_e32 v5, s0, v1
	v_mul_f32_e32 v4, 0x4f7ffffe, v4
	v_cvt_u32_f32_e32 v4, v4
	v_mul_lo_u32 v1, v3, v4
	v_mul_hi_u32 v1, v4, v1
	v_add_u32_e32 v1, v4, v1
	v_mul_hi_u32 v1, v5, v1
	v_mul_lo_u32 v3, v1, v2
	v_sub_u32_e32 v3, v5, v3
	v_add_u32_e32 v4, 1, v1
	v_cmp_ge_u32_e32 vcc, v3, v2
	s_nop 1
	v_cndmask_b32_e32 v1, v1, v4, vcc
	v_sub_u32_e32 v4, v3, v2
	v_cndmask_b32_e32 v3, v3, v4, vcc
	v_add_u32_e32 v4, 1, v1
	v_cmp_ge_u32_e32 vcc, v3, v2
	v_add_u32_e32 v3, 1, v5
	s_nop 0
	v_cndmask_b32_e32 v1, v1, v4, vcc
	v_mul_lo_u32 v4, v2, v1
	v_add_u32_e32 v2, v4, v2
	v_cmp_ne_u32_e32 vcc, v3, v2
	s_and_saveexec_b64 s[0:1], vcc
	s_xor_b64 s[6:7], exec, s[0:1]
	s_cbranch_execz .LBB0_325
	s_waitcnt lgkmcnt(0)
	s_add_u32 s14, s92, 0x4400
	s_addc_u32 s15, s93, 0
	v_mad_u32_u24 v1, v1, v0, v0
	v_mov_b32_e32 v0, 0
	global_load_dword v0, v0, s[14:15] sc1
	s_waitcnt vmcnt(0)
	v_cmp_lt_u32_e32 vcc, v0, v1
	s_and_saveexec_b64 s[8:9], vcc
	s_cbranch_execz .LBB0_324
	s_add_u32 s12, s92, 0x1200
	s_addc_u32 s13, s93, 0
	s_mov_b32 s0, 1
	s_mov_b64 s[16:17], 0
	v_mov_b32_e32 v0, 0
	s_branch .LBB0_315

.LBB0_319:
	global_load_dword v2, v0, s[14:15] sc1
	s_add_i32 s0, s0, 1
	s_mov_b64 s[22:23], -1
	s_waitcnt vmcnt(0)
	v_cmp_ge_u32_e32 vcc, v2, v1
	s_orn2_b64 s[20:21], vcc, exec
	s_branch .LBB0_314

.LBB0_328:
	s_or_b64 exec, exec, s[8:9]
	v_cvt_f32_u32_e32 v3, v0
	s_waitcnt vmcnt(0)
	v_readfirstlane_b32 s0, v2
	s_add_u32 s8, s92, 0x4500
	s_addc_u32 s9, s93, 0
	v_rcp_iflag_f32_e32 v3, v3
	v_add_u32_e32 v1, s0, v1
	v_add_u32_e32 v4, 1, v1
	s_mov_b64 s[12:13], -1
	v_mul_f32_e32 v2, 0x4f7ffffe, v3
	v_cvt_u32_f32_e32 v2, v2
	v_sub_u32_e32 v3, 0, v0
	v_mul_lo_u32 v3, v3, v2
	v_mul_hi_u32 v3, v2, v3
	v_add_u32_e32 v2, v2, v3
	v_mul_hi_u32 v2, v1, v2
	v_mul_lo_u32 v3, v2, v0
	v_sub_u32_e32 v1, v1, v3
	v_add_u32_e32 v5, 1, v2
	v_cmp_ge_u32_e32 vcc, v1, v0
	v_sub_u32_e32 v3, v1, v0
	s_nop 0
	v_cndmask_b32_e32 v2, v2, v5, vcc
	v_cndmask_b32_e32 v1, v1, v3, vcc
	v_add_u32_e32 v3, 1, v2
	v_cmp_ge_u32_e32 vcc, v1, v0
	s_nop 1
	v_cndmask_b32_e32 v2, v2, v3, vcc
	v_mul_lo_u32 v1, v0, v2
	v_add_u32_e32 v0, v1, v0
	v_cmp_ne_u32_e32 vcc, v4, v0
	v_mov_b32_e32 v2, v0
	v_mov_b64_e32 v[0:1], s[8:9]
	s_and_saveexec_b64 s[6:7], vcc
	s_cbranch_execz .LBB0_340
	v_mov_b32_e32 v0, 0
	global_load_dword v1, v0, s[8:9] offset:-256 sc1
	s_mov_b64 s[16:17], 0
	s_waitcnt vmcnt(0)
	v_cmp_lt_u32_e32 vcc, v1, v2
	s_and_saveexec_b64 s[14:15], vcc
	s_cbranch_execz .LBB0_339
	s_add_u32 s12, s92, 0x1200
	s_addc_u32 s13, s93, 0
	s_mov_b32 s0, 1
	s_branch .LBB0_332

.LBB0_336:
	global_load_dword v1, v0, s[8:9] offset:-256 sc1
	s_add_i32 s0, s0, 1
	s_mov_b64 s[20:21], -1
	s_waitcnt vmcnt(0)
	v_cmp_ge_u32_e32 vcc, v1, v2
	s_orn2_b64 s[30:31], vcc, exec
	s_branch .LBB0_331

.LBB0_677:
	s_or_b64 exec, exec, s[10:11]
	v_cvt_f32_u32_e32 v4, v2
	s_waitcnt vmcnt(0)
	v_readfirstlane_b32 s0, v3
	v_sub_u32_e32 v3, 0, v2
	v_rcp_iflag_f32_e32 v4, v4
	v_add_u32_e32 v5, s0, v1
	v_mul_f32_e32 v4, 0x4f7ffffe, v4
	v_cvt_u32_f32_e32 v4, v4
	v_mul_lo_u32 v1, v3, v4
	v_mul_hi_u32 v1, v4, v1
	v_add_u32_e32 v1, v4, v1
	v_mul_hi_u32 v1, v5, v1
	v_mul_lo_u32 v3, v1, v2
	v_sub_u32_e32 v3, v5, v3
	v_add_u32_e32 v4, 1, v1
	v_cmp_ge_u32_e32 vcc, v3, v2
	s_nop 1
	v_cndmask_b32_e32 v1, v1, v4, vcc
	v_sub_u32_e32 v4, v3, v2
	v_cndmask_b32_e32 v3, v3, v4, vcc
	v_add_u32_e32 v4, 1, v1
	v_cmp_ge_u32_e32 vcc, v3, v2
	v_add_u32_e32 v3, 1, v5
	s_nop 0
	v_cndmask_b32_e32 v1, v1, v4, vcc
	v_mul_lo_u32 v4, v2, v1
	v_add_u32_e32 v2, v4, v2
	v_cmp_ne_u32_e32 vcc, v3, v2
	s_and_saveexec_b64 s[0:1], vcc
	s_xor_b64 s[8:9], exec, s[0:1]
	s_cbranch_execz .LBB0_691
	s_waitcnt lgkmcnt(0)
	s_add_u32 s12, s66, 0x4400
	s_addc_u32 s13, s67, 0
	v_mad_u32_u24 v1, v1, v0, v0
	v_mov_b32_e32 v0, 0
	global_load_dword v0, v0, s[12:13] sc1
	s_waitcnt vmcnt(0)
	v_cmp_lt_u32_e32 vcc, v0, v1
	s_and_saveexec_b64 s[10:11], vcc
	s_cbranch_execz .LBB0_690
	s_mov_b32 s0, 1
	s_mov_b64 s[14:15], 0
	v_mov_b32_e32 v0, 0
	s_branch .LBB0_681

.LBB0_685:
	global_load_dword v2, v0, s[12:13] sc1
	s_add_i32 s0, s0, 1
	s_mov_b64 s[22:23], -1
	s_waitcnt vmcnt(0)
	v_cmp_ge_u32_e32 vcc, v2, v1
	s_orn2_b64 s[18:19], vcc, exec
	s_branch .LBB0_680

.LBB0_694:
	s_or_b64 exec, exec, s[10:11]
	v_cvt_f32_u32_e32 v3, v0
	s_waitcnt vmcnt(0)
	v_readfirstlane_b32 s0, v2
	s_add_u32 s10, s66, 0x4500
	s_addc_u32 s11, s67, 0
	v_rcp_iflag_f32_e32 v3, v3
	v_add_u32_e32 v1, s0, v1
	v_add_u32_e32 v4, 1, v1
	s_mov_b64 s[12:13], -1
	v_mul_f32_e32 v2, 0x4f7ffffe, v3
	v_cvt_u32_f32_e32 v2, v2
	v_sub_u32_e32 v3, 0, v0
	v_mul_lo_u32 v3, v3, v2
	v_mul_hi_u32 v3, v2, v3
	v_add_u32_e32 v2, v2, v3
	v_mul_hi_u32 v2, v1, v2
	v_mul_lo_u32 v3, v2, v0
	v_sub_u32_e32 v1, v1, v3
	v_add_u32_e32 v5, 1, v2
	v_cmp_ge_u32_e32 vcc, v1, v0
	v_sub_u32_e32 v3, v1, v0
	s_nop 0
	v_cndmask_b32_e32 v2, v2, v5, vcc
	v_cndmask_b32_e32 v1, v1, v3, vcc
	v_add_u32_e32 v3, 1, v2
	v_cmp_ge_u32_e32 vcc, v1, v0
	s_nop 1
	v_cndmask_b32_e32 v2, v2, v3, vcc
	v_mul_lo_u32 v1, v0, v2
	v_add_u32_e32 v0, v1, v0
	v_cmp_ne_u32_e32 vcc, v4, v0
	v_mov_b32_e32 v2, v0
	v_mov_b64_e32 v[0:1], s[10:11]
	s_and_saveexec_b64 s[8:9], vcc
	s_cbranch_execz .LBB0_706
	v_mov_b32_e32 v0, 0
	global_load_dword v1, v0, s[10:11] offset:-256 sc1
	s_mov_b64 s[14:15], 0
	s_waitcnt vmcnt(0)
	v_cmp_lt_u32_e32 vcc, v1, v2
	s_and_saveexec_b64 s[12:13], vcc
	s_cbranch_execz .LBB0_705
	s_mov_b32 s0, 1
	s_branch .LBB0_698

.LBB0_702:
	global_load_dword v1, v0, s[10:11] offset:-256 sc1
	s_add_i32 s0, s0, 1
	s_mov_b64 s[18:19], -1
	s_waitcnt vmcnt(0)
	v_cmp_ge_u32_e32 vcc, v1, v2
	s_orn2_b64 s[34:35], vcc, exec
	s_branch .LBB0_697
